# prologue: converted weights / expert tables stored with nt (written once, read phases later)
# speedup vs baseline: 1.0095x; 1.0002x over previous
; __device__ __forceinline__ unsigned cvt_pk_bf16(float lo, float hi) { unsigned r; asm("v_cvt_pk_bf16_f32 %0, %1, %2" : "=v"(r) : "v"(lo), "v"(hi)); return r; }
;     ...
;               if (sn0 + c4 < N && !(n0 >= pad_at && n0 < pad_at + pad_len)) v = *(const f32x4*)(s + (size_t)(k0 + rr) * N + sn0 + c4);
;               tile[rr * 65 + c4 + 0] = v[0]; tile[rr * 65 + c4 + 1] = v[1]; tile[rr * 65 + c4 + 2] = v[2]; tile[rr * 65 + c4 + 3] = v[3]; } }
;         __syncthreads();
;         { const int n = F.tid >> 3, kc = (F.tid & 7) * 8; float v[8];
; #pragma unroll
;           for (int e = 0; e < 8; ++e) { v[e] = tile[(kc + e) * 65 + n]; if (gain) v[e] *= gain[(size_t)mat * K + k0 + kc + e]; }
;           u32x4 w; w.x = cvt_pk_bf16(v[0], v[1]); w.y = cvt_pk_bf16(v[2], v[3]); w.z = cvt_pk_bf16(v[4], v[5]); w.w = cvt_pk_bf16(v[6], v[7]);
;           *(u32x4*)(d + (size_t)(n0 + n) * K + k0 + kc) = w; }
.LBB0_58:
	s_or_b64 exec, exec, s[6:7]
	s_waitcnt vmcnt(0)
	ds_write2_b32 v14, v0, v1 offset1:1
	ds_write2_b32 v15, v2, v3 offset1:1
	s_waitcnt lgkmcnt(0)
	s_barrier
	ds_read2_b32 v[0:1], v16 offset1:65
	ds_read2_b32 v[2:3], v16 offset0:130 offset1:195
	ds_read2_b32 v[18:19], v17 offset0:4 offset1:69
	ds_read2_b32 v[22:23], v17 offset0:134 offset1:199
	s_ashr_i32 s5, s4, 31
	s_mul_hi_i32 s7, s19, 0x1200000
	s_mul_i32 s19, s19, 0x1200000
	s_waitcnt lgkmcnt(3)
	v_cvt_pk_bf16_f32 v0, v0, v1
	s_waitcnt lgkmcnt(2)
	v_cvt_pk_bf16_f32 v1, v2, v3
	s_waitcnt lgkmcnt(1)
	v_cvt_pk_bf16_f32 v2, v18, v19
	v_add_u32_e32 v18, s18, v13
	s_add_u32 s6, s9, s19
	v_ashrrev_i32_e32 v19, 31, v18
	s_addc_u32 s7, s14, s7
	v_lshlrev_b64 v[18:19], 12, v[18:19]
	v_lshl_add_u64 v[18:19], s[6:7], 0, v[18:19]
	v_lshl_add_u64 v[18:19], s[4:5], 1, v[18:19]
	s_add_i32 s17, s17, s8
	v_lshl_add_u64 v[18:19], v[18:19], 0, v[10:11]
	s_cmpk_lt_i32 s17, 0x1200
	s_waitcnt lgkmcnt(0)
	v_cvt_pk_bf16_f32 v3, v22, v23
	global_store_dwordx4 v[18:19], v[0:3], off nt
	s_cbranch_scc0 .LBB0_63

; __device__ __forceinline__ unsigned cvt_pk_bf16(float lo, float hi) { unsigned r; asm("v_cvt_pk_bf16_f32 %0, %1, %2" : "=v"(r) : "v"(lo), "v"(hi)); return r; }
;     ...
;         { const int n = F.tid >> 3, kc = (F.tid & 7) * 8; float v[8];
; #pragma unroll
;           for (int e = 0; e < 8; ++e) { v[e] = tile[(kc + e) * 65 + n]; if (gain) v[e] *= gain[(size_t)mat * K + k0 + kc + e]; }
;           u32x4 w; w.x = cvt_pk_bf16(v[0], v[1]); w.y = cvt_pk_bf16(v[2], v[3]); w.z = cvt_pk_bf16(v[4], v[5]); w.w = cvt_pk_bf16(v[6], v[7]);
;           *(u32x4*)(d + (size_t)(n0 + n) * K + k0 + kc) = w; }
.LBB0_65:
	s_mul_hi_i32 s15, s20, 0x240000
	s_mul_i32 s20, s20, 0x240000
	s_add_u32 s20, s9, s20
	s_addc_u32 s21, s16, s15
	s_waitcnt lgkmcnt(6)
	v_cvt_pk_bf16_f32 v0, v0, v1
	s_waitcnt lgkmcnt(4)
	v_cvt_pk_bf16_f32 v1, v2, v3
	s_waitcnt lgkmcnt(2)
	v_cvt_pk_bf16_f32 v2, v4, v5
	s_waitcnt lgkmcnt(0)
	v_cvt_pk_bf16_f32 v3, v6, v7
	v_add_u32_e32 v6, s14, v13
	v_mov_b64_e32 v[4:5], s[20:21]
	v_mad_i64_i32 v[4:5], s[14:15], v6, s18, v[4:5]
	v_lshl_add_u64 v[4:5], s[12:13], 1, v[4:5]
	v_lshlrev_b32_e32 v10, 1, v12
	s_add_i32 s19, s19, s8
	v_lshl_add_u64 v[4:5], v[4:5], 0, v[10:11]
	s_cmpk_lt_i32 s19, 0x240
	global_store_dwordx4 v[4:5], v[0:3], off nt
	s_cbranch_scc0 .LBB0_82

; __device__ __forceinline__ unsigned cvt_pk_bf16(float lo, float hi) { unsigned r; asm("v_cvt_pk_bf16_f32 %0, %1, %2" : "=v"(r) : "v"(lo), "v"(hi)); return r; }
;     ...
;         { const int n = F.tid >> 3, kc = (F.tid & 7) * 8; float v[8];
; #pragma unroll
;           for (int e = 0; e < 8; ++e) { v[e] = tile[(kc + e) * 65 + n]; if (gain) v[e] *= gain[(size_t)mat * K + k0 + kc + e]; }
;           u32x4 w; w.x = cvt_pk_bf16(v[0], v[1]); w.y = cvt_pk_bf16(v[2], v[3]); w.z = cvt_pk_bf16(v[4], v[5]); w.w = cvt_pk_bf16(v[6], v[7]);
;           *(u32x4*)(d + (size_t)(n0 + n) * K + k0 + kc) = w; }
.LBB0_84:
	s_waitcnt lgkmcnt(6)
	v_cvt_pk_bf16_f32 v0, v0, v1
	s_lshl_b64 s[16:17], s[16:17], 21
	s_waitcnt lgkmcnt(4)
	v_cvt_pk_bf16_f32 v1, v2, v3
	s_waitcnt lgkmcnt(2)
	v_cvt_pk_bf16_f32 v2, v4, v5
	v_add_u32_e32 v4, s14, v13
	s_add_u32 s16, s9, s16
	v_ashrrev_i32_e32 v5, 31, v4
	s_addc_u32 s17, s18, s17
	v_lshlrev_b64 v[4:5], 10, v[4:5]
	v_lshl_add_u64 v[4:5], s[16:17], 0, v[4:5]
	v_lshl_add_u64 v[4:5], s[12:13], 1, v[4:5]
	v_lshlrev_b32_e32 v10, 1, v12
	s_add_i32 s19, s19, s8
	v_lshl_add_u64 v[4:5], v[4:5], 0, v[10:11]
	s_cmpk_lt_i32 s19, 0x200
	s_waitcnt lgkmcnt(0)
	v_cvt_pk_bf16_f32 v3, v6, v7
	global_store_dwordx4 v[4:5], v[0:3], off nt
	s_cbranch_scc0 .LBB0_101

; __device__ __forceinline__ unsigned cvt_pk_bf16(float lo, float hi) { unsigned r; asm("v_cvt_pk_bf16_f32 %0, %1, %2" : "=v"(r) : "v"(lo), "v"(hi)); return r; }
;     ...
;     for (int it = F.vcu; it < total; it += F.G) {
;         const int mat = it / per, rem = it % per, tn = rem / ntk, tk = rem % ntk, k0 = tk * 64, n0 = tn * 64;
;         const float* s = src + (size_t)mat * K * N; bf16_t* d = dst + (size_t)mat * Npad * K;
;         __syncthreads();
;         { const int r = F.tid >> 4, c4 = (F.tid & 15) * 4;
; #pragma unroll
;           for (int i = 0; i < 2; ++i) { const int rr = r + i * 32; f32x4 v = (f32x4){0.f, 0.f, 0.f, 0.f};
;               const int sn0 = n0 < pad_at ? n0 : n0 - pad_len;
;               if (sn0 + c4 < N && !(n0 >= pad_at && n0 < pad_at + pad_len)) v = *(const f32x4*)(s + (size_t)(k0 + rr) * N + sn0 + c4);
;               tile[rr * 65 + c4 + 0] = v[0]; tile[rr * 65 + c4 + 1] = v[1]; tile[rr * 65 + c4 + 2] = v[2]; tile[rr * 65 + c4 + 3] = v[3]; } }
;         __syncthreads();
;         { const int n = F.tid >> 3, kc = (F.tid & 7) * 8; float v[8];
; #pragma unroll
;           for (int e = 0; e < 8; ++e) { v[e] = tile[(kc + e) * 65 + n]; if (gain) v[e] *= gain[(size_t)mat * K + k0 + kc + e]; }
;           u32x4 w; w.x = cvt_pk_bf16(v[0], v[1]); w.y = cvt_pk_bf16(v[2], v[3]); w.z = cvt_pk_bf16(v[4], v[5]); w.w = cvt_pk_bf16(v[6], v[7]);
;           *(u32x4*)(d + (size_t)(n0 + n) * K + k0 + kc) = w; }
.LBB0_103:
	s_ashr_i32 s12, s9, 31
	s_lshr_b32 s12, s12, 22
	s_add_i32 s13, s9, s12
	s_ashr_i32 s12, s13, 10
	s_and_b32 s13, s13, 0xfc00
	s_sub_i32 s16, s9, s13
	s_sext_i32_i16 s17, s16
	s_bfe_u32 s17, s17, 0x5001a
	s_add_i32 s17, s16, s17
	s_sext_i32_i16 s18, s17
	s_and_b32 s17, s17, 0xffe0
	s_sub_i32 s16, s16, s17
	s_ashr_i32 s13, s12, 31
	s_lshl_b32 s17, s18, 1
	s_sext_i32_i16 s18, s16
	s_lshl_b64 s[14:15], s[12:13], 24
	s_and_b32 s16, s17, 0xffffffc0
	s_lshl_b32 s18, s18, 6
	s_waitcnt lgkmcnt(0)
	s_add_u32 s19, s4, s14
	s_addc_u32 s20, s5, s15
	s_ashr_i32 s17, s16, 31
	s_lshl_b64 s[14:15], s[16:17], 2
	v_add_u32_e32 v14, s18, v9
	s_add_u32 s14, s19, s14
	v_ashrrev_i32_e32 v15, 31, v14
	v_add_u32_e32 v16, 32, v14
	s_addc_u32 s15, s20, s15
	v_lshlrev_b64 v[14:15], 13, v[14:15]
	v_ashrrev_i32_e32 v17, 31, v16
	v_lshl_add_u64 v[18:19], s[14:15], 0, v[0:1]
	v_lshlrev_b64 v[16:17], 13, v[16:17]
	v_lshl_add_u64 v[26:27], v[18:19], 0, v[14:15]
	s_barrier
	v_lshl_add_u64 v[18:19], v[18:19], 0, v[16:17]
	global_load_dwordx4 v[14:17], v[26:27], off nt
	global_load_dwordx4 v[22:25], v[18:19], off nt
	v_add_u32_e32 v18, s16, v13
	s_ashr_i32 s19, s18, 31
	s_lshl_b64 s[12:13], s[12:13], 23
	v_ashrrev_i32_e32 v19, 31, v18
	s_add_u32 s12, s6, s12
	v_lshlrev_b64 v[18:19], 12, v[18:19]
	s_addc_u32 s13, s7, s13
	v_lshl_add_u64 v[18:19], s[12:13], 0, v[18:19]
	s_add_i32 s9, s9, s8
	v_lshl_add_u64 v[18:19], s[18:19], 1, v[18:19]
	s_cmpk_lt_i32 s9, 0x800
	v_lshl_add_u64 v[18:19], v[18:19], 0, v[2:3]
	s_waitcnt vmcnt(1)
	ds_write2_b32 v4, v14, v15 offset1:1
	ds_write2_b32 v5, v16, v17 offset1:1
	s_waitcnt vmcnt(0)
	ds_write2_b32 v6, v22, v23 offset1:1
	ds_write2_b32 v7, v24, v25 offset1:1
	s_waitcnt lgkmcnt(0)
	s_barrier
	ds_read2_b32 v[14:15], v10 offset1:65
	ds_read2_b32 v[16:17], v10 offset0:130 offset1:195
	ds_read2_b32 v[22:23], v11 offset0:4 offset1:69
	ds_read2_b32 v[24:25], v11 offset0:134 offset1:199
	s_waitcnt lgkmcnt(3)
	v_cvt_pk_bf16_f32 v14, v14, v15
	s_waitcnt lgkmcnt(2)
	v_cvt_pk_bf16_f32 v15, v16, v17
	s_waitcnt lgkmcnt(1)
	v_cvt_pk_bf16_f32 v16, v22, v23
	s_waitcnt lgkmcnt(0)
	v_cvt_pk_bf16_f32 v17, v24, v25
	global_store_dwordx4 v[18:19], v[14:17], off nt
	s_cbranch_scc1 .LBB0_103

; __device__ __forceinline__ unsigned cvt_pk_bf16(float lo, float hi) { unsigned r; asm("v_cvt_pk_bf16_f32 %0, %1, %2" : "=v"(r) : "v"(lo), "v"(hi)); return r; }
;     ...
;     for (int it = F.vcu; it < total; it += F.G) {
;         const int mat = it / per, rem = it % per, tn = rem / ntk, tk = rem % ntk, k0 = tk * 64, n0 = tn * 64;
;         const float* s = src + (size_t)mat * K * N; bf16_t* d = dst + (size_t)mat * Npad * K;
;         __syncthreads();
;         { const int r = F.tid >> 4, c4 = (F.tid & 15) * 4;
; #pragma unroll
;           for (int i = 0; i < 2; ++i) { const int rr = r + i * 32; f32x4 v = (f32x4){0.f, 0.f, 0.f, 0.f};
;               const int sn0 = n0 < pad_at ? n0 : n0 - pad_len;
;               if (sn0 + c4 < N && !(n0 >= pad_at && n0 < pad_at + pad_len)) v = *(const f32x4*)(s + (size_t)(k0 + rr) * N + sn0 + c4);
;               tile[rr * 65 + c4 + 0] = v[0]; tile[rr * 65 + c4 + 1] = v[1]; tile[rr * 65 + c4 + 2] = v[2]; tile[rr * 65 + c4 + 3] = v[3]; } }
;         __syncthreads();
;         { const int n = F.tid >> 3, kc = (F.tid & 7) * 8; float v[8];
; #pragma unroll
;           for (int e = 0; e < 8; ++e) { v[e] = tile[(kc + e) * 65 + n]; if (gain) v[e] *= gain[(size_t)mat * K + k0 + kc + e]; }
;           u32x4 w; w.x = cvt_pk_bf16(v[0], v[1]); w.y = cvt_pk_bf16(v[2], v[3]); w.z = cvt_pk_bf16(v[4], v[5]); w.w = cvt_pk_bf16(v[6], v[7]);
;           *(u32x4*)(d + (size_t)(n0 + n) * K + k0 + kc) = w; }
.LBB0_106:
	s_mul_hi_i32 s13, s12, 0x2aaaaaab
	s_lshr_b32 s14, s13, 31
	s_ashr_i32 s13, s13, 8
	s_add_i32 s13, s13, s14
	s_mul_i32 s14, s13, 0xfffffa00
	s_add_i32 s14, s12, s14
	s_bfe_u32 s16, s14, 0x5001a
	s_add_i32 s16, s14, s16
	s_sext_i32_i16 s18, s16
	s_and_b32 s16, s16, 0xffe0
	s_sub_i32 s14, s14, s16
	s_lshl_b32 s16, s18, 1
	s_sext_i32_i16 s18, s14
	s_mul_i32 s17, s13, 0x1800000
	s_and_b32 s14, s16, 0xffffffc0
	s_lshl_b32 s16, s18, 6
	s_mul_hi_i32 s15, s13, 0x1800000
	s_waitcnt lgkmcnt(0)
	s_add_u32 s17, s4, s17
	s_addc_u32 s20, s5, s15
	s_ashr_i32 s15, s14, 31
	s_lshl_b64 s[18:19], s[14:15], 2
	s_add_u32 s18, s17, s18
	s_addc_u32 s19, s20, s19
	v_add_u32_e32 v12, s16, v9
	v_lshl_add_u64 v[14:15], s[18:19], 0, v[0:1]
	v_add_u32_e32 v16, 32, v12
	v_mad_i64_i32 v[18:19], s[18:19], v12, s9, v[14:15]
	s_barrier
	v_mad_i64_i32 v[26:27], s[18:19], v16, s9, v[14:15]
	global_load_dwordx4 v[14:17], v[18:19], off nt
	global_load_dwordx4 v[22:25], v[26:27], off nt
	s_mul_hi_i32 s15, s13, 0xc00000
	s_mul_i32 s13, s13, 0xc00000
	v_add_u32_e32 v18, s14, v13
	s_ashr_i32 s17, s16, 31
	v_ashrrev_i32_e32 v19, 31, v18
	s_add_u32 s14, s6, s13
	v_lshlrev_b64 v[18:19], 12, v[18:19]
	s_addc_u32 s15, s7, s15
	v_lshl_add_u64 v[18:19], s[14:15], 0, v[18:19]
	s_add_i32 s12, s12, s8
	v_lshl_add_u64 v[18:19], s[16:17], 1, v[18:19]
	s_cmpk_lt_i32 s12, 0xc00
	v_lshl_add_u64 v[18:19], v[18:19], 0, v[2:3]
	s_waitcnt vmcnt(1)
	ds_write2_b32 v4, v14, v15 offset1:1
	ds_write2_b32 v5, v16, v17 offset1:1
	s_waitcnt vmcnt(0)
	ds_write2_b32 v6, v22, v23 offset1:1
	ds_write2_b32 v7, v24, v25 offset1:1
	s_waitcnt lgkmcnt(0)
	s_barrier
	ds_read2_b32 v[14:15], v10 offset1:65
	ds_read2_b32 v[16:17], v10 offset0:130 offset1:195
	ds_read2_b32 v[22:23], v11 offset0:4 offset1:69
	ds_read2_b32 v[24:25], v11 offset0:134 offset1:199
	s_waitcnt lgkmcnt(3)
	v_cvt_pk_bf16_f32 v14, v14, v15
	s_waitcnt lgkmcnt(2)
	v_cvt_pk_bf16_f32 v15, v16, v17
	s_waitcnt lgkmcnt(1)
	v_cvt_pk_bf16_f32 v16, v22, v23
	s_waitcnt lgkmcnt(0)
	v_cvt_pk_bf16_f32 v17, v24, v25
	global_store_dwordx4 v[18:19], v[14:17], off nt
	s_cbranch_scc1 .LBB0_106

; __device__ __forceinline__ unsigned cvt_pk_bf16(float lo, float hi) { unsigned r; asm("v_cvt_pk_bf16_f32 %0, %1, %2" : "=v"(r) : "v"(lo), "v"(hi)); return r; }
;     ...
;     for (int it = F.vcu; it < total; it += F.G) {
;         const int mat = it / per, rem = it % per, tn = rem / ntk, tk = rem % ntk, k0 = tk * 64, n0 = tn * 64;
;         const float* s = src + (size_t)mat * K * N; bf16_t* d = dst + (size_t)mat * Npad * K;
;         __syncthreads();
;         { const int r = F.tid >> 4, c4 = (F.tid & 15) * 4;
; #pragma unroll
;           for (int i = 0; i < 2; ++i) { const int rr = r + i * 32; f32x4 v = (f32x4){0.f, 0.f, 0.f, 0.f};
;               const int sn0 = n0 < pad_at ? n0 : n0 - pad_len;
;               if (sn0 + c4 < N && !(n0 >= pad_at && n0 < pad_at + pad_len)) v = *(const f32x4*)(s + (size_t)(k0 + rr) * N + sn0 + c4);
;               tile[rr * 65 + c4 + 0] = v[0]; tile[rr * 65 + c4 + 1] = v[1]; tile[rr * 65 + c4 + 2] = v[2]; tile[rr * 65 + c4 + 3] = v[3]; } }
;         __syncthreads();
;         { const int n = F.tid >> 3, kc = (F.tid & 7) * 8; float v[8];
; #pragma unroll
;           for (int e = 0; e < 8; ++e) { v[e] = tile[(kc + e) * 65 + n]; if (gain) v[e] *= gain[(size_t)mat * K + k0 + kc + e]; }
;           u32x4 w; w.x = cvt_pk_bf16(v[0], v[1]); w.y = cvt_pk_bf16(v[2], v[3]); w.z = cvt_pk_bf16(v[4], v[5]); w.w = cvt_pk_bf16(v[6], v[7]);
;           *(u32x4*)(d + (size_t)(n0 + n) * K + k0 + kc) = w; }
.LBB0_109:
	s_ashr_i32 s7, s6, 31
	s_lshr_b32 s7, s7, 22
	s_add_i32 s7, s6, s7
	s_ashr_i32 s12, s7, 10
	s_and_b32 s7, s7, 0xfc00
	s_sub_i32 s7, s6, s7
	s_sext_i32_i16 s9, s7
	s_bfe_u32 s9, s9, 0x5001a
	s_add_i32 s9, s7, s9
	s_sext_i32_i16 s16, s9
	s_and_b32 s9, s9, 0xffe0
	s_sub_i32 s7, s7, s9
	s_ashr_i32 s13, s12, 31
	s_lshl_b32 s9, s16, 1
	s_sext_i32_i16 s7, s7
	s_lshl_b64 s[14:15], s[12:13], 24
	s_and_b32 s16, s9, 0xffffffc0
	s_lshl_b32 s18, s7, 6
	s_waitcnt lgkmcnt(0)
	s_add_u32 s7, s2, s14
	s_addc_u32 s9, s3, s15
	s_ashr_i32 s17, s16, 31
	s_lshl_b64 s[14:15], s[16:17], 2
	v_add_u32_e32 v14, s18, v9
	s_add_u32 s14, s7, s14
	v_ashrrev_i32_e32 v15, 31, v14
	v_add_u32_e32 v16, 32, v14
	s_addc_u32 s15, s9, s15
	v_lshlrev_b64 v[14:15], 13, v[14:15]
	v_ashrrev_i32_e32 v17, 31, v16
	v_lshl_add_u64 v[18:19], s[14:15], 0, v[0:1]
	v_lshlrev_b64 v[16:17], 13, v[16:17]
	v_lshl_add_u64 v[26:27], v[18:19], 0, v[14:15]
	s_barrier
	v_lshl_add_u64 v[18:19], v[18:19], 0, v[16:17]
	global_load_dwordx4 v[14:17], v[26:27], off nt
	global_load_dwordx4 v[22:25], v[18:19], off nt
	v_add_u32_e32 v18, s16, v13
	s_ashr_i32 s19, s18, 31
	s_lshl_b64 s[12:13], s[12:13], 23
	v_ashrrev_i32_e32 v19, 31, v18
	s_add_u32 s12, s4, s12
	v_lshlrev_b64 v[18:19], 12, v[18:19]
	s_addc_u32 s13, s5, s13
	v_lshl_add_u64 v[18:19], s[12:13], 0, v[18:19]
	s_add_i32 s6, s6, s8
	v_lshl_add_u64 v[18:19], s[18:19], 1, v[18:19]
	s_cmpk_lt_i32 s6, 0x800
	v_lshl_add_u64 v[18:19], v[18:19], 0, v[2:3]
	s_waitcnt vmcnt(1)
	ds_write2_b32 v4, v14, v15 offset1:1
	ds_write2_b32 v5, v16, v17 offset1:1
	s_waitcnt vmcnt(0)
	ds_write2_b32 v6, v22, v23 offset1:1
	ds_write2_b32 v7, v24, v25 offset1:1
	s_waitcnt lgkmcnt(0)
	s_barrier
	ds_read2_b32 v[14:15], v10 offset1:65
	ds_read2_b32 v[16:17], v10 offset0:130 offset1:195
	ds_read2_b32 v[22:23], v11 offset0:4 offset1:69
	ds_read2_b32 v[24:25], v11 offset0:134 offset1:199
	s_waitcnt lgkmcnt(3)
	v_cvt_pk_bf16_f32 v14, v14, v15
	s_waitcnt lgkmcnt(2)
	v_cvt_pk_bf16_f32 v15, v16, v17
	s_waitcnt lgkmcnt(1)
	v_cvt_pk_bf16_f32 v16, v22, v23
	s_waitcnt lgkmcnt(0)
	v_cvt_pk_bf16_f32 v17, v24, v25
	global_store_dwordx4 v[18:19], v[14:17], off nt
	s_cbranch_scc1 .LBB0_109

; __device__ __forceinline__ unsigned cvt_pk_bf16(float lo, float hi) { unsigned r; asm("v_cvt_pk_bf16_f32 %0, %1, %2" : "=v"(r) : "v"(lo), "v"(hi)); return r; }
;     ...
;     for (int it = F.vcu; it < total; it += F.G) {
;         const int mat = it / per, rem = it % per, tn = rem / ntk, tk = rem % ntk, k0 = tk * 64, n0 = tn * 64;
;         const float* s = src + (size_t)mat * K * N; bf16_t* d = dst + (size_t)mat * Npad * K;
;         __syncthreads();
;         { const int r = F.tid >> 4, c4 = (F.tid & 15) * 4;
; #pragma unroll
;           for (int i = 0; i < 2; ++i) { const int rr = r + i * 32; f32x4 v = (f32x4){0.f, 0.f, 0.f, 0.f};
;               const int sn0 = n0 < pad_at ? n0 : n0 - pad_len;
;               if (sn0 + c4 < N && !(n0 >= pad_at && n0 < pad_at + pad_len)) v = *(const f32x4*)(s + (size_t)(k0 + rr) * N + sn0 + c4);
;               tile[rr * 65 + c4 + 0] = v[0]; tile[rr * 65 + c4 + 1] = v[1]; tile[rr * 65 + c4 + 2] = v[2]; tile[rr * 65 + c4 + 3] = v[3]; } }
;         __syncthreads();
;         { const int n = F.tid >> 3, kc = (F.tid & 7) * 8; float v[8];
; #pragma unroll
;           for (int e = 0; e < 8; ++e) { v[e] = tile[(kc + e) * 65 + n]; if (gain) v[e] *= gain[(size_t)mat * K + k0 + kc + e]; }
;           u32x4 w; w.x = cvt_pk_bf16(v[0], v[1]); w.y = cvt_pk_bf16(v[2], v[3]); w.z = cvt_pk_bf16(v[4], v[5]); w.w = cvt_pk_bf16(v[6], v[7]);
;           *(u32x4*)(d + (size_t)(n0 + n) * K + k0 + kc) = w; }
.LBB0_112:
	s_ashr_i32 s7, s6, 31
	s_lshr_b32 s7, s7, 22
	s_add_i32 s7, s6, s7
	s_ashr_i32 s12, s7, 10
	s_and_b32 s7, s7, 0xfc00
	s_sub_i32 s7, s6, s7
	s_sext_i32_i16 s9, s7
	s_bfe_u32 s9, s9, 0x5001a
	s_add_i32 s9, s7, s9
	s_sext_i32_i16 s16, s9
	s_and_b32 s9, s9, 0xffe0
	s_sub_i32 s7, s7, s9
	s_ashr_i32 s13, s12, 31
	s_lshl_b32 s9, s16, 1
	s_sext_i32_i16 s7, s7
	s_lshl_b64 s[14:15], s[12:13], 24
	s_and_b32 s16, s9, 0xffffffc0
	s_lshl_b32 s18, s7, 6
	s_waitcnt lgkmcnt(0)
	s_add_u32 s7, s2, s14
	s_addc_u32 s9, s3, s15
	s_ashr_i32 s17, s16, 31
	s_lshl_b64 s[14:15], s[16:17], 2
	v_add_u32_e32 v14, s18, v9
	s_add_u32 s14, s7, s14
	v_ashrrev_i32_e32 v15, 31, v14
	v_add_u32_e32 v16, 32, v14
	s_addc_u32 s15, s9, s15
	v_lshlrev_b64 v[14:15], 13, v[14:15]
	v_ashrrev_i32_e32 v17, 31, v16
	v_lshl_add_u64 v[18:19], s[14:15], 0, v[0:1]
	v_lshlrev_b64 v[16:17], 13, v[16:17]
	v_lshl_add_u64 v[22:23], v[18:19], 0, v[14:15]
	s_barrier
	v_lshl_add_u64 v[24:25], v[18:19], 0, v[16:17]
	global_load_dwordx4 v[14:17], v[22:23], off nt
	global_load_dwordx4 v[18:21], v[24:25], off nt
	v_add_u32_e32 v22, s16, v13
	s_ashr_i32 s19, s18, 31
	s_lshl_b64 s[12:13], s[12:13], 23
	v_ashrrev_i32_e32 v23, 31, v22
	s_add_u32 s12, s4, s12
	v_lshlrev_b64 v[22:23], 12, v[22:23]
	s_addc_u32 s13, s5, s13
	v_lshl_add_u64 v[22:23], s[12:13], 0, v[22:23]
	s_add_i32 s6, s6, s8
	v_lshl_add_u64 v[22:23], s[18:19], 1, v[22:23]
	s_cmpk_lt_i32 s6, 0x1000
	v_lshl_add_u64 v[22:23], v[22:23], 0, v[2:3]
	s_waitcnt vmcnt(1)
	ds_write2_b32 v4, v14, v15 offset1:1
	ds_write2_b32 v5, v16, v17 offset1:1
	s_waitcnt vmcnt(0)
	ds_write2_b32 v6, v18, v19 offset1:1
	ds_write2_b32 v7, v20, v21 offset1:1
	s_waitcnt lgkmcnt(0)
	s_barrier
	ds_read2_b32 v[14:15], v10 offset1:65
	ds_read2_b32 v[16:17], v10 offset0:130 offset1:195
	ds_read2_b32 v[18:19], v11 offset0:4 offset1:69
	ds_read2_b32 v[20:21], v11 offset0:134 offset1:199
	s_waitcnt lgkmcnt(3)
	v_cvt_pk_bf16_f32 v14, v14, v15
	s_waitcnt lgkmcnt(2)
	v_cvt_pk_bf16_f32 v15, v16, v17
	s_waitcnt lgkmcnt(1)
	v_cvt_pk_bf16_f32 v16, v18, v19
	s_waitcnt lgkmcnt(0)
	v_cvt_pk_bf16_f32 v17, v20, v21
	global_store_dwordx4 v[22:23], v[14:17], off nt
	s_cbranch_scc1 .LBB0_112

; __device__ __forceinline__ unsigned cvt_pk_bf16(float lo, float hi) { unsigned r; asm("v_cvt_pk_bf16_f32 %0, %1, %2" : "=v"(r) : "v"(lo), "v"(hi)); return r; }
; __device__ __forceinline__ void cvt_flat(const Ctx& F, const float* src, bf16_t* dst, size_t n8) {
;     for (size_t i = (size_t)F.vcu * 512 + F.tid; i < n8; i += (size_t)F.G * 512) {
;         const f32x4 a = *(const f32x4*)(src + i * 8), b = *(const f32x4*)(src + i * 8 + 4);
;         u32x4 w; w.x = cvt_pk_bf16(a[0], a[1]); w.y = cvt_pk_bf16(a[2], a[3]); w.z = cvt_pk_bf16(b[0], b[1]); w.w = cvt_pk_bf16(b[2], b[3]);
;         *(u32x4*)(dst + i * 8) = w;
;     }
; }
.LBB0_115:
	global_load_dwordx4 v[6:9], v[4:5], off offset:-16 nt
	global_load_dwordx4 v[10:13], v[4:5], off nt
	v_lshl_add_u64 v[0:1], v[0:1], 0, s[4:5]
	v_cmp_lt_u64_e32 vcc, s[16:17], v[0:1]
	v_lshl_add_u64 v[4:5], v[4:5], 0, s[12:13]
	s_or_b64 s[14:15], vcc, s[14:15]
	s_waitcnt vmcnt(1)
	v_cvt_pk_bf16_f32 v6, v6, v7
	v_cvt_pk_bf16_f32 v7, v8, v9
	s_waitcnt vmcnt(0)
	v_cvt_pk_bf16_f32 v8, v10, v11
	v_cvt_pk_bf16_f32 v9, v12, v13
	global_store_dwordx4 v[2:3], v[6:9], off nt
	v_lshl_add_u64 v[2:3], v[2:3], 0, s[6:7]
	s_andn2_b64 exec, exec, s[14:15]
	s_cbranch_execnz .LBB0_115

; __device__ __forceinline__ void cvt_rows_fp6(const Ctx& F, const float* src, unsigned char* dst, float* descale, int R) {
;     ...
;     for (int row = F.vcu * 8 + F.wid; row < R; row += F.G * 8) {
;         const float* s = src + (size_t)row * DM + F.lane * 4; f32x4 v[8]; float am = 0.f;
; #pragma unroll
;         for (int i = 0; i < 8; ++i) { v[i] = *(const f32x4*)(s + i * 256);
; #pragma unroll
;             for (int e = 0; e < 4; ++e) am = fmaxf(am, fabsf(v[i][e])); }
;         am = wave_max(am);
;         const float sc = am > 0.f ? 7.f / am : 1.f;
; #pragma unroll
;         for (int i = 0; i < 8; ++i)
; #pragma unroll
;             for (int e = 0; e < 4; ++e) stg[F.lane * 33 + permL[i * 4 + e]] = v[i][e] * sc;
;         asm volatile("s_waitcnt lgkmcnt(0)" ::: "memory"); __builtin_amdgcn_wave_barrier(); asm volatile("" ::: "memory");
;         v16f lo, hi;
; #pragma unroll
;         for (int i = 0; i < 16; ++i) { lo[i] = stg[F.lane * 33 + i]; hi[i] = stg[F.lane * 33 + 16 + i]; }
;         asm volatile("s_waitcnt lgkmcnt(0)" ::: "memory"); __builtin_amdgcn_wave_barrier(); asm volatile("" ::: "memory");
;         const v6u w = __builtin_amdgcn_cvt_scalef32_2xpk16_fp6_f32(lo, hi, 1.0f);
;         unsigned char* d = dst + (size_t)row * EROW;
;         *(u32x4*)(d + F.lane * 16) = (u32x4){w[0], w[1], w[2], w[3]}; *(u32x2*)(d + 1024 + F.lane * 8) = (u32x2){w[4], w[5]};
.LBB0_537:
	global_load_dwordx4 v[52:55], v[74:75], off offset:-4096 nt
	global_load_dwordx4 v[48:51], v[74:75], off offset:-3072 nt
	global_load_dwordx4 v[44:47], v[74:75], off offset:-2048 nt
	global_load_dwordx4 v[40:43], v[74:75], off offset:-1024 nt
	global_load_dwordx4 v[36:39], v[74:75], off nt
	global_load_dwordx4 v[32:35], v[74:75], off offset:1024 nt
	global_load_dwordx4 v[56:59], v[74:75], off offset:2048 nt
	global_load_dwordx4 v[60:63], v[74:75], off offset:3072 nt
	ds_read_b128 v[80:83], v67
	ds_read_b128 v[84:87], v67 offset:16
	ds_read_b128 v[88:91], v67 offset:32
	ds_read_b128 v[92:95], v67 offset:48
	ds_read_b128 v[96:99], v67 offset:64
	ds_read_b128 v[100:103], v67 offset:80
	ds_read_b128 v[104:107], v67 offset:96
	ds_read_b128 v[108:111], v67 offset:112
	s_waitcnt lgkmcnt(7)
	v_lshl_add_u32 v80, v80, 2, v78
	v_lshl_add_u32 v81, v81, 2, v78
	v_lshl_add_u32 v82, v82, 2, v78
	v_lshl_add_u32 v83, v83, 2, v78
	s_waitcnt lgkmcnt(6)
	v_lshl_add_u32 v84, v84, 2, v78
	v_lshl_add_u32 v85, v85, 2, v78
	v_lshl_add_u32 v86, v86, 2, v78
	v_lshl_add_u32 v87, v87, 2, v78
	s_waitcnt lgkmcnt(5)
	v_lshl_add_u32 v88, v88, 2, v78
	v_lshl_add_u32 v89, v89, 2, v78
	v_lshl_add_u32 v90, v90, 2, v78
	v_lshl_add_u32 v91, v91, 2, v78
	s_waitcnt lgkmcnt(4)
	v_lshl_add_u32 v92, v92, 2, v78
	v_lshl_add_u32 v93, v93, 2, v78
	v_lshl_add_u32 v94, v94, 2, v78
	v_lshl_add_u32 v95, v95, 2, v78
	s_waitcnt lgkmcnt(3)
	v_lshl_add_u32 v96, v96, 2, v78
	v_lshl_add_u32 v97, v97, 2, v78
	v_lshl_add_u32 v98, v98, 2, v78
	v_lshl_add_u32 v99, v99, 2, v78
	s_waitcnt lgkmcnt(2)
	v_lshl_add_u32 v100, v100, 2, v78
	v_lshl_add_u32 v101, v101, 2, v78
	v_lshl_add_u32 v102, v102, 2, v78
	v_lshl_add_u32 v103, v103, 2, v78
	s_waitcnt lgkmcnt(1)
	v_lshl_add_u32 v104, v104, 2, v78
	v_lshl_add_u32 v105, v105, 2, v78
	v_lshl_add_u32 v106, v106, 2, v78
	s_waitcnt vmcnt(7)
	v_max3_f32 v79, |v52|, 0, |v53|
	v_max3_f32 v79, v79, |v54|, |v55|
	s_waitcnt vmcnt(6)
	v_max3_f32 v79, v79, |v48|, |v49|
	v_max3_f32 v79, v79, |v50|, |v51|
	s_waitcnt vmcnt(5)
	v_max3_f32 v79, v79, |v44|, |v45|
	v_max3_f32 v79, v79, |v46|, |v47|
	s_waitcnt vmcnt(4)
	v_max3_f32 v79, v79, |v40|, |v41|
	v_max3_f32 v79, v79, |v42|, |v43|
	s_waitcnt vmcnt(3)
	v_max3_f32 v79, v79, |v36|, |v37|
	v_max3_f32 v79, v79, |v38|, |v39|
	s_waitcnt vmcnt(2)
	v_max3_f32 v79, v79, |v32|, |v33|
	v_max3_f32 v79, v79, |v34|, |v35|
	s_waitcnt vmcnt(1)
	v_max3_f32 v79, v79, |v56|, |v57|
	v_max3_f32 v79, v79, |v58|, |v59|
	s_waitcnt vmcnt(0)
	v_max3_f32 v79, v79, |v60|, |v61|
	v_max3_f32 v79, v79, |v62|, |v63|
	ds_swizzle_b32 v112, v79 offset:swizzle(SWAP,16)
	s_waitcnt lgkmcnt(0)
	v_max_f32_e32 v112, v112, v112
	v_max_f32_e32 v79, v79, v112
	ds_swizzle_b32 v112, v79 offset:swizzle(SWAP,8)
	s_waitcnt lgkmcnt(0)
	v_max_f32_e32 v112, v112, v112
	v_max_f32_e32 v79, v79, v112
	ds_swizzle_b32 v112, v79 offset:swizzle(SWAP,4)
	s_waitcnt lgkmcnt(0)
	v_max_f32_e32 v112, v112, v112
	v_max_f32_e32 v79, v79, v112
	ds_swizzle_b32 v112, v79 offset:swizzle(SWAP,2)
	s_waitcnt lgkmcnt(0)
	v_max_f32_e32 v112, v112, v112
	v_max_f32_e32 v79, v79, v112
	ds_swizzle_b32 v112, v79 offset:swizzle(SWAP,1)
	s_waitcnt lgkmcnt(0)
	v_max_f32_e32 v112, v112, v112
	v_max_f32_e32 v79, v79, v112
	v_mov_b32_e32 v112, v79
	s_nop 1
	v_permlane32_swap_b32_e32 v79, v112
	v_max_f32_e32 v112, v112, v112
	v_max_f32_e32 v79, v79, v79
	v_max_f32_e32 v79, v79, v112
	v_div_scale_f32 v112, s[22:23], v79, v79, s7
	v_rcp_f32_e32 v113, v112
	v_div_scale_f32 v114, vcc, s7, v79, s7
	v_fma_f32 v115, -v112, v113, 1.0
	v_fmac_f32_e32 v113, v115, v113
	v_mul_f32_e32 v115, v114, v113
	v_fma_f32 v116, -v112, v115, v114
	v_fmac_f32_e32 v115, v116, v113
	v_fma_f32 v112, -v112, v115, v114
	v_div_fmas_f32 v112, v112, v113, v115
	v_div_fixup_f32 v112, v112, v79, s7
	v_cmp_lt_f32_e32 vcc, 0, v79
	s_nop 1
	v_cndmask_b32_e32 v112, 1.0, v112, vcc
	v_mul_f32_e32 v52, v52, v112
	v_mul_f32_e32 v32, v32, v112
	v_mul_f32_e32 v53, v53, v112
	v_mul_f32_e32 v54, v54, v112
	v_mul_f32_e32 v55, v55, v112
	v_mul_f32_e32 v48, v48, v112
	v_mul_f32_e32 v49, v49, v112
	v_mul_f32_e32 v50, v50, v112
	v_mul_f32_e32 v51, v51, v112
	v_mul_f32_e32 v44, v44, v112
	v_mul_f32_e32 v45, v45, v112
	v_mul_f32_e32 v46, v46, v112
	v_mul_f32_e32 v47, v47, v112
	v_mul_f32_e32 v40, v40, v112
	v_mul_f32_e32 v41, v41, v112
	v_mul_f32_e32 v42, v42, v112
	v_mul_f32_e32 v43, v43, v112
	v_mul_f32_e32 v36, v36, v112
	v_mul_f32_e32 v37, v37, v112
	v_mul_f32_e32 v38, v38, v112
	v_mul_f32_e32 v39, v39, v112
	v_mul_f32_e32 v33, v33, v112
	v_mul_f32_e32 v34, v34, v112
	v_mul_f32_e32 v35, v35, v112
	v_mul_f32_e32 v56, v56, v112
	v_mul_f32_e32 v57, v57, v112
	v_mul_f32_e32 v58, v58, v112
	v_mul_f32_e32 v59, v59, v112
	ds_write_b32 v80, v52
	ds_write_b32 v81, v53
	ds_write_b32 v82, v54
	ds_write_b32 v83, v55
	ds_write_b32 v84, v48
	ds_write_b32 v85, v49
	ds_write_b32 v86, v50
	ds_write_b32 v87, v51
	ds_write_b32 v88, v44
	ds_write_b32 v89, v45
	ds_write_b32 v90, v46
	ds_write_b32 v91, v47
	ds_write_b32 v92, v40
	ds_write_b32 v93, v41
	ds_write_b32 v94, v42
	ds_write_b32 v95, v43
	ds_write_b32 v96, v36
	ds_write_b32 v97, v37
	ds_write_b32 v98, v38
	ds_write_b32 v99, v39
	ds_write_b32 v100, v32
	ds_write_b32 v101, v33
	ds_write_b32 v102, v34
	ds_write_b32 v103, v35
	ds_write_b32 v104, v56
	ds_write_b32 v105, v57
	ds_write_b32 v106, v58
	v_lshl_add_u32 v32, v107, 2, v78
	ds_write_b32 v32, v59
	v_mul_f32_e32 v32, v60, v112
	v_lshl_add_u32 v34, v108, 2, v78
	v_mul_f32_e32 v33, v61, v112
	ds_write_b32 v34, v32
	v_lshl_add_u32 v32, v109, 2, v78
	ds_write_b32 v32, v33
	v_mul_f32_e32 v32, v62, v112
	v_lshl_add_u32 v34, v110, 2, v78
	v_mul_f32_e32 v33, v63, v112
	ds_write_b32 v34, v32
	v_lshl_add_u32 v32, v111, 2, v78
	ds_write_b32 v32, v33
	s_waitcnt lgkmcnt(0)
	ds_read2_b32 v[32:33], v78 offset1:1
	ds_read2_b32 v[34:35], v78 offset0:2 offset1:3
	ds_read2_b32 v[36:37], v78 offset0:4 offset1:5
	ds_read2_b32 v[38:39], v78 offset0:6 offset1:7
	ds_read2_b32 v[48:49], v78 offset0:16 offset1:17
	ds_read2_b32 v[50:51], v78 offset0:18 offset1:19
	ds_read2_b32 v[52:53], v78 offset0:20 offset1:21
	ds_read2_b32 v[54:55], v78 offset0:22 offset1:23
	ds_read2_b32 v[40:41], v78 offset0:8 offset1:9
	ds_read2_b32 v[42:43], v78 offset0:10 offset1:11
	ds_read2_b32 v[44:45], v78 offset0:12 offset1:13
	ds_read2_b32 v[46:47], v78 offset0:14 offset1:15
	ds_read2_b32 v[56:57], v78 offset0:24 offset1:25
	ds_read2_b32 v[58:59], v78 offset0:26 offset1:27
	ds_read2_b32 v[60:61], v78 offset0:28 offset1:29
	ds_read2_b32 v[62:63], v78 offset0:30 offset1:31
	s_waitcnt lgkmcnt(0)
	s_waitcnt lgkmcnt(0)
	v_cvt_scalef32_2xpk16_fp6_f32 v[32:37], v[32:47], v[48:63], 1.0
	global_store_dwordx4 v[72:73], v[32:35], off nt
	s_nop 1
	v_lshl_add_u64 v[32:33], v[72:73], 0, v[70:71]
	global_store_dwordx2 v[32:33], v[36:37], off offset:1024 nt
	s_and_saveexec_b64 s[22:23], s[2:3]
	s_cbranch_execz .LBB0_536
; __device__ __forceinline__ void cvt_rows_fp6(const Ctx& F, const float* src, unsigned char* dst, float* descale, int R) {
;     ...
;         if (F.lane == 0) descale[row] = (am > 0.f ? am * (1.f / 7.f) : 1.f) / (fac > 0.f ? fac : 1.f);
	v_mul_f32_e32 v32, 0x3e124925, v79
	v_cndmask_b32_e32 v32, 1.0, v32, vcc
	v_div_scale_f32 v33, s[30:31], v77, v77, v32
	v_rcp_f32_e32 v34, v33
	v_div_scale_f32 v35, vcc, v32, v77, v32
	v_fma_f32 v36, -v33, v34, 1.0
	v_fmac_f32_e32 v34, v36, v34
	v_mul_f32_e32 v36, v35, v34
	v_fma_f32 v37, -v33, v36, v35
	v_fmac_f32_e32 v36, v37, v34
	v_fma_f32 v33, -v33, v36, v35
	v_div_fmas_f32 v33, v33, v34, v36
	v_div_fixup_f32 v32, v33, v77, v32
	global_store_dword v69, v32, s[14:15] nt
	s_branch .LBB0_536

; __device__ __forceinline__ void cvt_rows_fp6(const Ctx& F, const float* src, unsigned char* dst, float* descale, int R) {
;     ...
;     for (int row = F.vcu * 8 + F.wid; row < R; row += F.G * 8) {
;         const float* s = src + (size_t)row * DM + F.lane * 4; f32x4 v[8]; float am = 0.f;
; #pragma unroll
;         for (int i = 0; i < 8; ++i) { v[i] = *(const f32x4*)(s + i * 256);
; #pragma unroll
;             for (int e = 0; e < 4; ++e) am = fmaxf(am, fabsf(v[i][e])); }
;         am = wave_max(am);
;         const float sc = am > 0.f ? 7.f / am : 1.f;
; #pragma unroll
;         for (int i = 0; i < 8; ++i)
; #pragma unroll
;             for (int e = 0; e < 4; ++e) stg[F.lane * 33 + permL[i * 4 + e]] = v[i][e] * sc;
;         asm volatile("s_waitcnt lgkmcnt(0)" ::: "memory"); __builtin_amdgcn_wave_barrier(); asm volatile("" ::: "memory");
;         v16f lo, hi;
; #pragma unroll
;         for (int i = 0; i < 16; ++i) { lo[i] = stg[F.lane * 33 + i]; hi[i] = stg[F.lane * 33 + 16 + i]; }
;         asm volatile("s_waitcnt lgkmcnt(0)" ::: "memory"); __builtin_amdgcn_wave_barrier(); asm volatile("" ::: "memory");
;         const v6u w = __builtin_amdgcn_cvt_scalef32_2xpk16_fp6_f32(lo, hi, 1.0f);
;         unsigned char* d = dst + (size_t)row * EROW;
;         *(u32x4*)(d + F.lane * 16) = (u32x4){w[0], w[1], w[2], w[3]}; *(u32x2*)(d + 1024 + F.lane * 8) = (u32x2){w[4], w[5]};
.LBB0_960:
	global_load_dwordx4 v[4:7], v[36:37], off offset:-4096 nt
	global_load_dwordx4 v[8:11], v[36:37], off offset:-3072 nt
	global_load_dwordx4 v[12:15], v[36:37], off offset:-2048 nt
	global_load_dwordx4 v[16:19], v[36:37], off offset:-1024 nt
	global_load_dwordx4 v[20:23], v[36:37], off nt
	global_load_dwordx4 v[24:27], v[36:37], off offset:1024 nt
	global_load_dwordx4 v[28:31], v[36:37], off offset:2048 nt
	global_load_dwordx4 v[0:3], v[36:37], off offset:3072 nt
	ds_read_b128 v[42:45], v39
	ds_read_b128 v[46:49], v39 offset:16
	ds_read_b128 v[50:53], v39 offset:32
	ds_read_b128 v[54:57], v39 offset:48
	ds_read_b128 v[58:61], v39 offset:64
	ds_read_b128 v[62:65], v39 offset:80
	ds_read_b128 v[66:69], v39 offset:96
	ds_read_b128 v[70:73], v39 offset:112
	s_waitcnt lgkmcnt(7)
	v_lshl_add_u32 v42, v42, 2, v38
	v_lshl_add_u32 v43, v43, 2, v38
	v_lshl_add_u32 v44, v44, 2, v38
	v_lshl_add_u32 v45, v45, 2, v38
	s_waitcnt lgkmcnt(6)
	v_lshl_add_u32 v46, v46, 2, v38
	v_lshl_add_u32 v47, v47, 2, v38
	v_lshl_add_u32 v48, v48, 2, v38
	v_lshl_add_u32 v49, v49, 2, v38
	s_waitcnt lgkmcnt(5)
	v_lshl_add_u32 v50, v50, 2, v38
	v_lshl_add_u32 v51, v51, 2, v38
	v_lshl_add_u32 v52, v52, 2, v38
	v_lshl_add_u32 v53, v53, 2, v38
	s_waitcnt lgkmcnt(4)
	v_lshl_add_u32 v54, v54, 2, v38
	v_lshl_add_u32 v55, v55, 2, v38
	v_lshl_add_u32 v56, v56, 2, v38
	v_lshl_add_u32 v57, v57, 2, v38
	s_waitcnt lgkmcnt(3)
	v_lshl_add_u32 v58, v58, 2, v38
	v_lshl_add_u32 v59, v59, 2, v38
	v_lshl_add_u32 v60, v60, 2, v38
	v_lshl_add_u32 v61, v61, 2, v38
	s_waitcnt lgkmcnt(2)
	v_lshl_add_u32 v62, v62, 2, v38
	v_lshl_add_u32 v63, v63, 2, v38
	v_lshl_add_u32 v64, v64, 2, v38
	v_lshl_add_u32 v65, v65, 2, v38
	s_waitcnt lgkmcnt(1)
	v_lshl_add_u32 v66, v66, 2, v38
	v_lshl_add_u32 v67, v67, 2, v38
	v_lshl_add_u32 v68, v68, 2, v38
	s_waitcnt vmcnt(7)
	v_max3_f32 v41, |v4|, 0, |v5|
	v_max3_f32 v41, v41, |v6|, |v7|
	s_waitcnt vmcnt(6)
	v_max3_f32 v41, v41, |v8|, |v9|
	v_max3_f32 v41, v41, |v10|, |v11|
	s_waitcnt vmcnt(5)
	v_max3_f32 v41, v41, |v12|, |v13|
	v_max3_f32 v41, v41, |v14|, |v15|
	s_waitcnt vmcnt(4)
	v_max3_f32 v41, v41, |v16|, |v17|
	v_max3_f32 v41, v41, |v18|, |v19|
	s_waitcnt vmcnt(3)
	v_max3_f32 v41, v41, |v20|, |v21|
	v_max3_f32 v41, v41, |v22|, |v23|
	s_waitcnt vmcnt(2)
	v_max3_f32 v41, v41, |v24|, |v25|
	v_max3_f32 v41, v41, |v26|, |v27|
	s_waitcnt vmcnt(1)
	v_max3_f32 v41, v41, |v28|, |v29|
	v_max3_f32 v41, v41, |v30|, |v31|
	s_waitcnt vmcnt(0)
	v_max3_f32 v41, v41, |v0|, |v1|
	v_max3_f32 v41, v41, |v2|, |v3|
	ds_swizzle_b32 v74, v41 offset:swizzle(SWAP,16)
	s_waitcnt lgkmcnt(0)
	v_max_f32_e32 v74, v74, v74
	v_max_f32_e32 v41, v41, v74
	ds_swizzle_b32 v74, v41 offset:swizzle(SWAP,8)
	s_waitcnt lgkmcnt(0)
	v_max_f32_e32 v74, v74, v74
	v_max_f32_e32 v41, v41, v74
	ds_swizzle_b32 v74, v41 offset:swizzle(SWAP,4)
	s_waitcnt lgkmcnt(0)
	v_max_f32_e32 v74, v74, v74
	v_max_f32_e32 v41, v41, v74
	ds_swizzle_b32 v74, v41 offset:swizzle(SWAP,2)
	s_waitcnt lgkmcnt(0)
	v_max_f32_e32 v74, v74, v74
	v_max_f32_e32 v41, v41, v74
	ds_swizzle_b32 v74, v41 offset:swizzle(SWAP,1)
	s_waitcnt lgkmcnt(0)
	v_max_f32_e32 v74, v74, v74
	v_max_f32_e32 v41, v41, v74
	v_mov_b32_e32 v74, v41
	s_nop 1
	v_permlane32_swap_b32_e32 v41, v74
	v_max_f32_e32 v74, v74, v74
	v_max_f32_e32 v41, v41, v41
	v_max_f32_e32 v41, v41, v74
	v_div_scale_f32 v74, s[16:17], v41, v41, s7
	v_rcp_f32_e32 v75, v74
	v_div_scale_f32 v76, vcc, s7, v41, s7
	v_fma_f32 v78, -v74, v75, 1.0
	v_fmac_f32_e32 v75, v78, v75
	v_mul_f32_e32 v78, v76, v75
	v_fma_f32 v79, -v74, v78, v76
	v_fmac_f32_e32 v78, v79, v75
	v_fma_f32 v74, -v74, v78, v76
	v_div_fmas_f32 v74, v74, v75, v78
	v_div_fixup_f32 v74, v74, v41, s7
	v_cmp_lt_f32_e32 vcc, 0, v41
	s_nop 1
	v_cndmask_b32_e32 v74, 1.0, v74, vcc
	v_mul_f32_e32 v4, v4, v74
	v_mul_f32_e32 v5, v5, v74
	v_mul_f32_e32 v6, v6, v74
	v_mul_f32_e32 v7, v7, v74
	v_mul_f32_e32 v8, v8, v74
	v_mul_f32_e32 v9, v9, v74
	v_mul_f32_e32 v10, v10, v74
	v_mul_f32_e32 v11, v11, v74
	v_mul_f32_e32 v12, v12, v74
	v_mul_f32_e32 v13, v13, v74
	v_mul_f32_e32 v14, v14, v74
	v_mul_f32_e32 v15, v15, v74
	v_mul_f32_e32 v16, v16, v74
	v_mul_f32_e32 v17, v17, v74
	v_mul_f32_e32 v18, v18, v74
	v_mul_f32_e32 v19, v19, v74
	v_mul_f32_e32 v20, v20, v74
	v_mul_f32_e32 v21, v21, v74
	v_mul_f32_e32 v22, v22, v74
	v_mul_f32_e32 v23, v23, v74
	v_mul_f32_e32 v24, v24, v74
	v_mul_f32_e32 v25, v25, v74
	v_mul_f32_e32 v26, v26, v74
	v_mul_f32_e32 v27, v27, v74
	v_mul_f32_e32 v28, v28, v74
	v_mul_f32_e32 v29, v29, v74
	v_mul_f32_e32 v30, v30, v74
	v_mul_f32_e32 v31, v31, v74
	ds_write_b32 v42, v4
	ds_write_b32 v43, v5
	ds_write_b32 v44, v6
	ds_write_b32 v45, v7
	ds_write_b32 v46, v8
	ds_write_b32 v47, v9
	ds_write_b32 v48, v10
	ds_write_b32 v49, v11
	ds_write_b32 v50, v12
	ds_write_b32 v51, v13
	ds_write_b32 v52, v14
	ds_write_b32 v53, v15
	ds_write_b32 v54, v16
	ds_write_b32 v55, v17
	ds_write_b32 v56, v18
	ds_write_b32 v57, v19
	ds_write_b32 v58, v20
	ds_write_b32 v59, v21
	ds_write_b32 v60, v22
	ds_write_b32 v61, v23
	ds_write_b32 v62, v24
	ds_write_b32 v63, v25
	ds_write_b32 v64, v26
	ds_write_b32 v65, v27
	ds_write_b32 v66, v28
	ds_write_b32 v67, v29
	ds_write_b32 v68, v30
	v_lshl_add_u32 v4, v69, 2, v38
	ds_write_b32 v4, v31
	v_mul_f32_e32 v0, v0, v74
	v_lshl_add_u32 v4, v70, 2, v38
	v_mul_f32_e32 v1, v1, v74
	ds_write_b32 v4, v0
	v_lshl_add_u32 v0, v71, 2, v38
	ds_write_b32 v0, v1
	v_mul_f32_e32 v0, v2, v74
	v_lshl_add_u32 v2, v72, 2, v38
	v_mul_f32_e32 v1, v3, v74
	ds_write_b32 v2, v0
	v_lshl_add_u32 v0, v73, 2, v38
	ds_write_b32 v0, v1
	s_waitcnt lgkmcnt(0)
	ds_read2_b32 v[0:1], v38 offset1:1
	ds_read2_b32 v[2:3], v38 offset0:2 offset1:3
	ds_read2_b32 v[4:5], v38 offset0:4 offset1:5
	ds_read2_b32 v[6:7], v38 offset0:6 offset1:7
	ds_read2_b32 v[16:17], v38 offset0:16 offset1:17
	ds_read2_b32 v[18:19], v38 offset0:18 offset1:19
	ds_read2_b32 v[20:21], v38 offset0:20 offset1:21
	ds_read2_b32 v[22:23], v38 offset0:22 offset1:23
	ds_read2_b32 v[8:9], v38 offset0:8 offset1:9
	ds_read2_b32 v[10:11], v38 offset0:10 offset1:11
	ds_read2_b32 v[12:13], v38 offset0:12 offset1:13
	ds_read2_b32 v[14:15], v38 offset0:14 offset1:15
	ds_read2_b32 v[24:25], v38 offset0:24 offset1:25
	ds_read2_b32 v[26:27], v38 offset0:26 offset1:27
	ds_read2_b32 v[28:29], v38 offset0:28 offset1:29
	ds_read2_b32 v[30:31], v38 offset0:30 offset1:31
	s_waitcnt lgkmcnt(0)
	s_waitcnt lgkmcnt(0)
	v_cvt_scalef32_2xpk16_fp6_f32 v[0:5], v[0:15], v[16:31], 1.0
	global_store_dwordx4 v[34:35], v[0:3], off nt
	s_nop 1
	v_lshl_add_u64 v[0:1], v[34:35], 0, v[32:33]
	global_store_dwordx2 v[0:1], v[4:5], off offset:1024 nt
	s_and_saveexec_b64 s[16:17], s[2:3]
	s_cbranch_execz .LBB0_959
; __device__ __forceinline__ void cvt_rows_fp6(const Ctx& F, const float* src, unsigned char* dst, float* descale, int R) {
;     ...
;         if (F.lane == 0) descale[row] = (am > 0.f ? am * (1.f / 7.f) : 1.f) / (fac > 0.f ? fac : 1.f);
	v_mul_f32_e32 v0, 0x3e124925, v41
	v_cndmask_b32_e32 v0, 1.0, v0, vcc
	v_div_scale_f32 v1, s[18:19], v77, v77, v0
	v_rcp_f32_e32 v2, v1
	v_div_scale_f32 v3, vcc, v0, v77, v0
	v_fma_f32 v4, -v1, v2, 1.0
	v_fmac_f32_e32 v2, v4, v2
	v_mul_f32_e32 v4, v3, v2
	v_fma_f32 v5, -v1, v4, v3
	v_fmac_f32_e32 v4, v5, v2
	v_fma_f32 v1, -v1, v4, v3
	v_div_fmas_f32 v1, v1, v2, v4
	v_div_fixup_f32 v0, v1, v77, v0
	global_store_dword v40, v0, s[12:13] nt
	s_branch .LBB0_959
